# static s_setprio 1 for waves 4-7 in the retention sample tile loop and the hyena sample e-loop
# speedup vs baseline: 1.0369x; 1.0011x over previous
.LBB0_722:
	v_mov_b32_e32 v161, v78
	v_add_u32_e32 v126, 0x3f80, v77
	v_cmp_gt_u32_e32 vcc, 64, v161
	v_mad_u32_u24 v162, v161, s83, v65
	s_nop 0
	v_cndmask_b32_e32 v127, v214, v162, vcc
	ds_read_b128 v[142:145], v126
	ds_read_b128 v[170:173], v127
	ds_read_b128 v[146:149], v126 offset:32
	ds_read_b128 v[174:177], v127 offset:32
	ds_read_b128 v[150:153], v126 offset:64
	ds_read_b128 v[178:181], v127 offset:64
	ds_read_b128 v[154:157], v126 offset:96
	ds_read_b128 v[182:185], v127 offset:96
	s_movk_i32 s0, 47
	v_readfirstlane_b32 s1, v192
	s_nop 0
	s_cmp_ge_u32 s1, 0x100
	s_cbranch_scc0 .Lhy_prio_skip
	s_setprio 1
.Lhy_prio_skip:
.Lhy_s_loop:
	v_add_u32_e32 v161, -1, v161
	v_add_u32_e32 v126, 0xffffff80, v126
	v_cmp_gt_u32_e32 vcc, 64, v161
	v_mad_u32_u24 v162, v161, s83, v65
	s_nop 0
	v_cndmask_b32_e32 v160, v214, v162, vcc
	ds_read_b128 v[216:219], v126
	ds_read_b128 v[232:235], v160
	ds_read_b128 v[220:223], v126 offset:32
	ds_read_b128 v[236:239], v160 offset:32
	ds_read_b128 v[224:227], v126 offset:64
	ds_read_b128 v[240:243], v160 offset:64
	ds_read_b128 v[228:231], v126 offset:96
	ds_read_b128 v[244:247], v160 offset:96
	s_waitcnt lgkmcnt(8)
	v_mfma_f32_32x32x16_bf16 v[0:15], v[142:145], v[170:173], v[0:15]
	v_mfma_f32_32x32x16_bf16 v[0:15], v[146:149], v[174:177], v[0:15]
	v_mfma_f32_32x32x16_bf16 v[0:15], v[150:153], v[178:181], v[0:15]
	v_mfma_f32_32x32x16_bf16 v[0:15], v[154:157], v[182:185], v[0:15]
	v_add_u32_e32 v161, -1, v161
	v_add_u32_e32 v126, 0xffffff80, v126
	v_cmp_gt_u32_e32 vcc, 64, v161
	v_mad_u32_u24 v162, v161, s83, v65
	s_nop 0
	v_cndmask_b32_e32 v127, v214, v162, vcc
	ds_read_b128 v[142:145], v126
	ds_read_b128 v[170:173], v127
	ds_read_b128 v[146:149], v126 offset:32
	ds_read_b128 v[174:177], v127 offset:32
	ds_read_b128 v[150:153], v126 offset:64
	ds_read_b128 v[178:181], v127 offset:64
	ds_read_b128 v[154:157], v126 offset:96
	ds_read_b128 v[182:185], v127 offset:96
	s_waitcnt lgkmcnt(8)
	v_mfma_f32_32x32x16_bf16 v[0:15], v[216:219], v[232:235], v[0:15]
	v_mfma_f32_32x32x16_bf16 v[0:15], v[220:223], v[236:239], v[0:15]
	v_mfma_f32_32x32x16_bf16 v[0:15], v[224:227], v[240:243], v[0:15]
	v_mfma_f32_32x32x16_bf16 v[0:15], v[228:231], v[244:247], v[0:15]
	s_add_i32 s0, s0, -1
	s_cmp_lg_u32 s0, 0
	s_cbranch_scc1 .Lhy_s_loop
	s_waitcnt lgkmcnt(0)
	v_mfma_f32_32x32x16_bf16 v[0:15], v[142:145], v[170:173], v[0:15]
	v_mfma_f32_32x32x16_bf16 v[0:15], v[146:149], v[174:177], v[0:15]
	v_mfma_f32_32x32x16_bf16 v[0:15], v[150:153], v[178:181], v[0:15]
	v_mfma_f32_32x32x16_bf16 v[0:15], v[154:157], v[182:185], v[0:15]
	s_setprio 0
	s_and_b64 s[0:1], s[88:89], exec
	s_cselect_b32 s0, s90, s82
	s_lshl_b32 s0, s0, 1
	s_add_u32 s0, s48, s0
	s_addc_u32 s1, s49, 0
	v_lshl_add_u64 v[96:97], v[22:23], 1, s[0:1]
	v_mov_b32_e32 v61, v112
	v_lshl_add_u64 v[96:97], v[96:97], 0, v[60:61]
	v_mov_b32_e32 v63, v112
	v_lshl_add_u64 v[96:97], v[96:97], 0, v[62:63]
	s_mov_b64 s[0:1], 0x4000
	v_lshl_add_u64 v[98:99], v[96:97], 0, s[0:1]
	s_movk_i32 s0, 0x4000
	v_add_co_u32_e32 v96, vcc, s0, v96
	s_nop 1
	v_addc_co_u32_e32 v97, vcc, 0, v97, vcc
	s_barrier
	global_load_dwordx2 v[96:97], v[96:97], off
	s_movk_i32 s0, 0x400
	s_mov_b64 s[88:89], 0
	s_and_b64 vcc, exec, s[12:13]
	s_waitcnt vmcnt(0)
	v_lshlrev_b32_e32 v100, 16, v96
	v_and_b32_e32 v101, 0xffff0000, v96
	v_lshlrev_b32_e32 v96, 16, v97
	v_and_b32_e32 v97, 0xffff0000, v97
	v_pk_mul_f32 v[0:1], v[0:1], v[100:101]
	v_pk_mul_f32 v[2:3], v[2:3], v[96:97]
	v_cvt_pk_bf16_f32 v0, v0, v1
	v_cvt_pk_bf16_f32 v1, v2, v3
	global_load_dwordx2 v[2:3], v[98:99], off offset:16
	s_waitcnt vmcnt(0)
	v_lshlrev_b32_e32 v96, 16, v2
	v_and_b32_e32 v97, 0xffff0000, v2
	v_pk_mul_f32 v[4:5], v[4:5], v[96:97]
	s_nop 0
	v_cvt_pk_bf16_f32 v2, v4, v5
	v_lshlrev_b32_e32 v4, 16, v3
	v_and_b32_e32 v5, 0xffff0000, v3
	v_pk_mul_f32 v[4:5], v[6:7], v[4:5]
	s_nop 0
	v_cvt_pk_bf16_f32 v3, v4, v5
	ds_write2_b64 v76, v[0:1], v[2:3] offset1:2
	global_load_dwordx2 v[0:1], v[98:99], off offset:32
	s_waitcnt vmcnt(0)
	v_lshlrev_b32_e32 v2, 16, v0
	v_and_b32_e32 v3, 0xffff0000, v0
	v_pk_mul_f32 v[2:3], v[8:9], v[2:3]
	s_nop 0
	v_cvt_pk_bf16_f32 v0, v2, v3
	v_lshlrev_b32_e32 v2, 16, v1
	v_and_b32_e32 v3, 0xffff0000, v1
	v_pk_mul_f32 v[2:3], v[10:11], v[2:3]
	s_nop 0
	v_cvt_pk_bf16_f32 v1, v2, v3
	global_load_dwordx2 v[2:3], v[98:99], off offset:48
	s_waitcnt vmcnt(0)
	v_lshlrev_b32_e32 v4, 16, v2
	v_and_b32_e32 v5, 0xffff0000, v2
	v_pk_mul_f32 v[4:5], v[12:13], v[4:5]
	s_nop 0
	v_cvt_pk_bf16_f32 v2, v4, v5
	v_lshlrev_b32_e32 v4, 16, v3
	v_and_b32_e32 v5, 0xffff0000, v3
	v_pk_mul_f32 v[4:5], v[14:15], v[4:5]
	s_nop 0
	v_cvt_pk_bf16_f32 v3, v4, v5
	ds_write2_b64 v76, v[0:1], v[2:3] offset0:4 offset1:6
	s_waitcnt lgkmcnt(0)
	s_barrier
	s_cbranch_vccz .LBB0_565
	s_lshl_b32 s0, s90, 1
	v_readlane_b32 s2, v254, 39
	v_readlane_b32 s3, v254, 40
	s_add_u32 s0, s2, s0
	s_addc_u32 s1, s3, 0
	v_lshlrev_b32_e32 v0, 1, v16
	v_mov_b32_e32 v1, v112
	v_lshl_add_u64 v[0:1], s[0:1], 0, v[0:1]
	s_mov_b64 s[0:1], 0x4000
	v_lshl_add_u64 v[4:5], v[0:1], 0, s[0:1]
	v_add_u32_e32 v0, v17, v67
	ds_read_b128 v[0:3], v0
	v_lshl_add_u64 v[6:7], v[50:51], 1, v[4:5]
	s_mov_b32 s96, 0
	s_movk_i32 s71, 0x90
	v_lshl_add_u64 v[4:5], v[42:43], 1, v[4:5]
	s_waitcnt lgkmcnt(0)
	global_store_dwordx4 v[6:7], v[0:3], off
	v_readlane_b32 s88, v255, 25
	s_movk_i32 s97, 0x5eed
	v_add_u32_e32 v0, v17, v66
	ds_read_b128 v[0:3], v0
	v_readlane_b32 s38, v253, 1
	s_movk_i32 s74, 0x2400
	s_movk_i32 s64, 0x1fff
	v_readlane_b32 s89, v255, 26
	s_waitcnt lgkmcnt(0)
	global_store_dwordx4 v[4:5], v[0:3], off
	s_barrier
	v_readlane_b32 s39, v253, 2
	s_branch .LBB0_466

.LBB0_802:
	s_or_b64 exec, exec, s[0:1]
	s_mov_b32 s0, 0xbfb8aa3b
	s_waitcnt vmcnt(0)
	v_mul_f32_e64 v195, |v0|, s0
	v_mul_f32_e64 v201, |v1|, s0
	s_or_b32 s0, s7, s4
	s_mul_hi_u32 s1, s0, 0x3000
	s_mulk_i32 s20, 0x3000
	s_add_i32 s1, s1, s20
	s_mulk_i32 s0, 0x3000
	v_readlane_b32 s8, v254, 39
	v_readlane_b32 s9, v254, 40
	s_add_u32 s0, s8, s0
	s_addc_u32 s1, s9, s1
	s_add_u32 s0, s0, s5
	s_mul_hi_u32 s21, s7, 0x3000
	s_addc_u32 s1, s1, 0
	s_add_i32 s21, s21, s20
	s_mulk_i32 s7, 0x3000
	s_add_u32 s7, s8, s7
	s_addc_u32 s21, s9, s21
	s_add_u32 s20, s7, s5
	s_addc_u32 s21, s21, 0
	s_ashr_i32 s7, s6, 31
	s_lshl_b64 s[6:7], s[6:7], 11
	s_or_b32 s5, s6, s5
	v_mov_b32_e32 v4, v192
	s_or_b32 s5, s5, s26
	s_mul_i32 s6, s7, 0x2400
	v_and_b32_e32 v189, 31, v4
	s_mul_hi_u32 s7, s5, 0x2400
	v_mul_u32_u24_e32 v0, 0x1800, v189
	s_add_i32 s7, s7, s6
	s_mulk_i32 s5, 0x2400
	v_readlane_b32 s8, v254, 41
	v_bfe_u32 v5, v4, 5, 1
	v_lshlrev_b32_e32 v0, 1, v0
	v_mov_b32_e32 v1, v112
	v_ashrrev_i32_e32 v193, 6, v4
	v_readlane_b32 s9, v254, 42
	s_add_u32 s6, s8, s5
	v_lshl_add_u64 v[0:1], s[0:1], 0, v[0:1]
	v_lshlrev_b32_e32 v2, 4, v5
	v_mov_b32_e32 v3, v112
	v_readfirstlane_b32 s0, v193
	s_addc_u32 s7, s9, s7
	v_lshl_add_u64 v[0:1], v[0:1], 0, v[2:3]
	s_lshl_b32 s5, s0, 3
	global_load_dwordx4 v[142:145], v[0:1], off
	global_load_dwordx4 v[138:141], v[0:1], off offset:32
	global_load_dwordx4 v[134:137], v[0:1], off offset:64
	global_load_dwordx4 v[130:133], v[0:1], off offset:96
	global_load_dwordx4 v[126:129], v[0:1], off offset:128
	global_load_dwordx4 v[122:125], v[0:1], off offset:160
	global_load_dwordx4 v[118:121], v[0:1], off offset:192
	global_load_dwordx4 v[114:117], v[0:1], off offset:224
	global_load_dwordx4 v[108:111], v[0:1], off offset:256
	global_load_dwordx4 v[104:107], v[0:1], off offset:288
	global_load_dwordx4 v[100:103], v[0:1], off offset:320
	global_load_dwordx4 v[96:99], v[0:1], off offset:352
	global_load_dwordx4 v[92:95], v[0:1], off offset:384
	global_load_dwordx4 v[88:91], v[0:1], off offset:416
	global_load_dwordx4 v[84:87], v[0:1], off offset:448
	global_load_dwordx4 v[80:83], v[0:1], off offset:480
	v_or_b32_e32 v1, s5, v5
	v_bitop3_b32 v2, s5, v4, v5 bitop3:0x36
	s_movk_i32 s28, 0x1800
	v_mul_lo_u32 v1, v1, s28
	v_lshlrev_b32_e32 v2, 3, v2
	s_movk_i32 s27, 0xf8
	v_bfe_u32 v0, v4, 3, 3
	v_and_or_b32 v1, v2, s27, v1
	v_bfe_u32 v2, v4, 4, 2
	s_lshl_b32 s1, s0, 2
	v_lshlrev_b32_e32 v146, 1, v1
	v_lshl_or_b32 v1, s0, 5, v0
	v_xor_b32_e32 v2, v2, v4
	s_movk_i32 s29, 0x1200
	v_mul_lo_u32 v1, v1, s29
	v_lshlrev_b32_e32 v2, 3, v2
	s_or_b32 s5, s1, 1
	v_and_or_b32 v1, v2, 56, v1
	s_lshl_b32 s26, s5, 1
	v_lshlrev_b32_e32 v148, 1, v1
	v_or_b32_e32 v1, s26, v5
	v_bitop3_b32 v2, s26, v4, v5 bitop3:0x36
	v_mul_lo_u32 v1, v1, s28
	v_lshlrev_b32_e32 v2, 3, v2
	v_and_or_b32 v1, v2, s27, v1
	v_lshlrev_b32_e32 v150, 1, v1
	v_lshl_or_b32 v1, s5, 3, v0
	v_lshrrev_b32_e32 v2, 1, v1
	v_xor_b32_e32 v2, v2, v4
	v_mul_lo_u32 v1, v1, s29
	v_lshlrev_b32_e32 v2, 3, v2
	s_or_b32 s5, s1, 2
	v_and_or_b32 v1, v2, 56, v1
	s_lshl_b32 s26, s5, 1
	v_lshlrev_b32_e32 v152, 1, v1
	v_or_b32_e32 v1, s26, v5
	v_bitop3_b32 v2, s26, v4, v5 bitop3:0x36
	v_mul_lo_u32 v1, v1, s28
	v_lshlrev_b32_e32 v2, 3, v2
	v_and_or_b32 v1, v2, s27, v1
	v_lshlrev_b32_e32 v154, 1, v1
	v_lshl_or_b32 v1, s5, 3, v0
	v_lshrrev_b32_e32 v2, 1, v1
	v_xor_b32_e32 v2, v2, v4
	v_mul_lo_u32 v1, v1, s29
	v_lshlrev_b32_e32 v2, 3, v2
	s_or_b32 s1, s1, 3
	v_and_or_b32 v1, v2, 56, v1
	s_lshl_b32 s5, s1, 1
	v_lshlrev_b32_e32 v156, 1, v1
	v_or_b32_e32 v1, s5, v5
	v_bitop3_b32 v2, s5, v4, v5 bitop3:0x36
	v_mul_lo_u32 v1, v1, s28
	v_lshlrev_b32_e32 v2, 3, v2
	v_and_or_b32 v1, v2, s27, v1
	v_lshl_or_b32 v0, s1, 3, v0
	v_lshlrev_b32_e32 v158, 1, v1
	v_lshrrev_b32_e32 v1, 1, v0
	v_xor_b32_e32 v1, v1, v4
	v_mul_lo_u32 v0, v0, s29
	v_lshlrev_b32_e32 v1, 3, v1
	v_and_or_b32 v0, v1, 56, v0
	v_lshlrev_b32_e32 v160, 1, v0
	v_mul_f32_e32 v0, 0xc1000000, v195
	v_exp_f32_e64 v2, -v195
	v_exp_f32_e32 v0, v0
	v_exp_f32_e32 v1, v201
	v_mov_b32_e32 v147, v112
	v_readfirstlane_b32 s30, v2
	v_readfirstlane_b32 s31, v0
	v_mul_f32_e32 v0, 0x41000000, v201
	v_mul_f32_e64 v170, s30, s30
	v_readfirstlane_b32 s34, v1
	v_exp_f32_e32 v0, v0
	v_readfirstlane_b32 s1, v170
	v_mul_f32_e64 v172, s34, s34
	s_mov_b64 s[26:27], 0x800
	v_mov_b32_e32 v2, s1
	v_readfirstlane_b32 s1, v172
	v_readfirstlane_b32 s35, v0
	v_mov_b32_e32 v151, v112
	v_mov_b32_e32 v1, s1
	s_lshl_b32 s1, s0, 12
	v_mul_f32_e32 v173, s34, v1
	v_lshl_add_u64 v[0:1], s[20:21], 0, v[146:147]
	s_add_i32 s36, s1, 0
	v_lshl_add_u64 v[0:1], v[0:1], 0, s[26:27]
	s_mov_b32 m0, s36
	v_mov_b32_e32 v155, v112
	global_load_lds_dwordx4 v[0:1], off
	v_lshl_add_u64 v[0:1], s[20:21], 0, v[150:151]
	v_lshl_add_u64 v[0:1], v[0:1], 0, s[26:27]
	s_add_i32 m0, s36, 0x400
	v_mov_b32_e32 v159, v112
	global_load_lds_dwordx4 v[0:1], off
	v_lshl_add_u64 v[0:1], s[20:21], 0, v[154:155]
	v_lshl_add_u64 v[0:1], v[0:1], 0, s[26:27]
	s_add_i32 m0, s36, 0x800
	v_or_b32_e32 v162, s4, v189
	global_load_lds_dwordx4 v[0:1], off
	v_lshl_add_u64 v[0:1], s[20:21], 0, v[158:159]
	v_lshl_add_u64 v[0:1], v[0:1], 0, s[26:27]
	s_add_i32 m0, s36, 0xc00
	s_lshl_b32 s0, s0, 11
	global_load_lds_dwordx4 v[0:1], off
	s_add_i32 m0, s36, 0x8000
	v_bitop3_b32 v0, v5, v4, 31 bitop3:0x78
	global_load_lds_dwordx4 v148, s[6:7]
	s_add_i32 m0, s36, 0x8400
	v_lshlrev_b32_e32 v216, 4, v0
	global_load_lds_dwordx4 v152, s[6:7]
	s_add_i32 m0, s36, 0x8800
	v_lshrrev_b32_e32 v0, 1, v4
	global_load_lds_dwordx4 v156, s[6:7]
	s_add_i32 m0, s36, 0x8c00
	v_bitop3_b32 v0, v0, v5, 7 bitop3:0x6c
	global_load_lds_dwordx4 v160, s[6:7]
	v_lshlrev_b32_e32 v213, 4, v0
	v_sub_u32_e32 v0, 0x1000, v162
	v_cvt_f32_u32_e32 v0, v0
	v_add_u32_e32 v1, 1, v162
	v_cvt_f32_u32_e32 v1, v1
	s_add_i32 s56, 0, 0x20000
	s_add_i32 s37, s56, s0
	s_xor_b32 s0, s0, 0x2000
	s_add_i32 s24, s24, s25
	s_lshl_b32 s20, s22, 3
	v_lshlrev_b32_e32 v190, 2, v5
	s_add_i32 s56, s56, s0
	s_lshl_b32 s0, s64, 14
	s_lshl_b32 s28, s64, 6
	v_mul_f32_e32 v214, v201, v0
	v_add_u32_e32 v0, s24, v189
	s_mul_i32 s1, s23, 0x3000
	s_and_b32 s20, s20, 0x600
	s_waitcnt vmcnt(0)
	s_lshl_b32 s57, s64, 5
	s_or_b32 s27, s28, 32
	v_mul_f32_e32 v218, v195, v1
	s_or_b32 s55, s4, 31
	s_sub_i32 s26, 64, s28
	s_sub_i32 s5, 0x60, s28
	s_add_i32 s29, s0, 0
	v_sub_u32_e32 v1, v0, v190
	s_or_b32 s1, s1, s20
	v_and_b32_e32 v191, 63, v4
	v_or_b32_e32 v219, s57, v190
	v_subrev_u32_e32 v220, s57, v1
	s_mul_hi_i32 s0, s23, 0x3000
	s_add_u32 s20, s84, s1
	v_mov_b32_e32 v48, 0
	v_mul_f32_e32 v171, s30, v2
	v_mov_b32_e32 v149, v112
	v_mov_b32_e32 v153, v112
	v_mov_b32_e32 v157, v112
	v_mov_b32_e32 v161, v112
	v_lshlrev_b32_e32 v215, 9, v189
	v_lshlrev_b32_e32 v217, 4, v191
	v_lshlrev_b32_e32 v202, 7, v189
	v_mov_b32_e32 v113, v162
	v_subrev_u32_e32 v221, 27, v220
	v_subrev_u32_e32 v222, 26, v220
	v_sub_u32_e32 v223, v219, v0
	s_addc_u32 s21, s42, s0
	s_mov_b32 s63, 0
	s_mov_b64 s[22:23], 0x80
	s_mov_b32 s58, 0
	s_mov_b32 s59, 0
	s_mov_b32 s62, 0
	v_mov_b32_e32 v49, v48
	v_mov_b32_e32 v50, v48
	v_mov_b32_e32 v51, v48
	v_mov_b32_e32 v52, v48
	v_mov_b32_e32 v53, v48
	v_mov_b32_e32 v54, v48
	v_mov_b32_e32 v55, v48
	v_mov_b32_e32 v56, v48
	v_mov_b32_e32 v57, v48
	v_mov_b32_e32 v58, v48
	v_mov_b32_e32 v59, v48
	v_mov_b32_e32 v60, v48
	v_mov_b32_e32 v61, v48
	v_mov_b32_e32 v62, v48
	v_mov_b32_e32 v63, v48
	v_mov_b32_e32 v32, v48
	v_mov_b32_e32 v33, v48
	v_mov_b32_e32 v34, v48
	v_mov_b32_e32 v35, v48
	v_mov_b32_e32 v36, v48
	v_mov_b32_e32 v37, v48
	v_mov_b32_e32 v38, v48
	v_mov_b32_e32 v39, v48
	v_mov_b32_e32 v40, v48
	v_mov_b32_e32 v41, v48
	v_mov_b32_e32 v42, v48
	v_mov_b32_e32 v43, v48
	v_mov_b32_e32 v44, v48
	v_mov_b32_e32 v45, v48
	v_mov_b32_e32 v46, v48
	v_mov_b32_e32 v47, v48
	v_mov_b32_e32 v16, v48
	v_mov_b32_e32 v17, v48
	v_mov_b32_e32 v18, v48
	v_mov_b32_e32 v19, v48
	v_mov_b32_e32 v20, v48
	v_mov_b32_e32 v21, v48
	v_mov_b32_e32 v22, v48
	v_mov_b32_e32 v23, v48
	v_mov_b32_e32 v24, v48
	v_mov_b32_e32 v25, v48
	v_mov_b32_e32 v26, v48
	v_mov_b32_e32 v27, v48
	v_mov_b32_e32 v28, v48
	v_mov_b32_e32 v29, v48
	v_mov_b32_e32 v30, v48
	v_mov_b32_e32 v31, v48
	v_mov_b32_e32 v0, v48
	v_mov_b32_e32 v1, v48
	v_mov_b32_e32 v2, v48
	v_mov_b32_e32 v3, v48
	v_mov_b32_e32 v4, v48
	v_mov_b32_e32 v5, v48
	v_mov_b32_e32 v6, v48
	v_mov_b32_e32 v7, v48
	v_mov_b32_e32 v8, v48
	v_mov_b32_e32 v9, v48
	v_mov_b32_e32 v10, v48
	v_mov_b32_e32 v11, v48
	v_mov_b32_e32 v12, v48
	v_mov_b32_e32 v13, v48
	v_mov_b32_e32 v14, v48
	v_mov_b32_e32 v15, v48
	s_waitcnt vmcnt(0) lgkmcnt(0)
	s_barrier
	s_cmp_lg_u32 s64, 0
	s_cbranch_scc0 .Lret_prio_skip
	s_setprio 1
.Lret_prio_skip:
	s_branch .LBB0_804
.LBB0_803:
	s_nop 6
	v_mul_f32_e32 v71, v79, v188
	v_cvt_pk_bf16_f32 v64, v174, v175
	v_cvt_pk_bf16_f32 v65, v176, v177
	v_cvt_pk_bf16_f32 v66, v178, v179
	v_cvt_pk_bf16_f32 v67, v180, v181
	v_add_u32_e32 v175, s37, v217
	v_cvt_pk_bf16_f32 v68, v182, v183
	v_cvt_pk_bf16_f32 v69, v184, v185
	v_cvt_pk_bf16_f32 v70, v186, v187
	v_cvt_pk_bf16_f32 v71, v194, v71
	ds_write_b128 v175, v[64:67]
	ds_write_b128 v175, v[68:71] offset:1024
	v_add_u32_e32 v224, s0, v202
	v_add_u32_e32 v224, v224, v213
	v_add_u32_e32 v224, 0x8000, v224
	v_xor_b32_e32 v225, s28, v224
	ds_read_b128 v[228:231], v225
	ds_read_b128 v[232:235], v225 offset:4096
	ds_read_b128 v[236:239], v225 offset:8192
	ds_read_b128 v[240:243], v225 offset:12288
	v_xor_b32_e32 v225, s27, v224
	ds_read_b128 v[244:247], v225
	ds_read_b128 v[248:251], v225 offset:4096
	ds_read_b128 v[72:75], v225 offset:8192
	ds_read_b128 v[76:79], v225 offset:12288
	v_add_u32_e32 v174, s56, v217
	s_add_i32 s59, s59, 64
	s_sub_i32 s58, s58, 64
	s_add_u32 s22, s22, 0x80
	s_addc_u32 s23, s23, 0
	s_add_u32 s20, s20, 0xc0000
	s_addc_u32 s21, s21, 0
	s_mov_b32 s63, s61
	s_mov_b32 s62, s60
	s_cmpk_eq_i32 s59, 0x11c0
	s_waitcnt lgkmcnt(4)
	v_mfma_f32_32x32x16_bf16 v[48:63], v[228:231], v[64:67], v[48:63]
	v_mfma_f32_32x32x16_bf16 v[32:47], v[232:235], v[64:67], v[32:47]
	v_mfma_f32_32x32x16_bf16 v[16:31], v[236:239], v[64:67], v[16:31]
	v_mfma_f32_32x32x16_bf16 v[0:15], v[240:243], v[64:67], v[0:15]
	s_waitcnt lgkmcnt(0)
	s_barrier
	ds_read_b128 v[176:179], v174
	ds_read_b128 v[180:183], v174 offset:1024
	v_xor_b32_e32 v225, s26, v224
	ds_read_b128 v[228:231], v225
	ds_read_b128 v[232:235], v225 offset:4096
	ds_read_b128 v[236:239], v225 offset:8192
	ds_read_b128 v[240:243], v225 offset:12288
	v_mfma_f32_32x32x16_bf16 v[48:63], v[244:247], v[68:71], v[48:63]
	v_mfma_f32_32x32x16_bf16 v[32:47], v[248:251], v[68:71], v[32:47]
	v_mfma_f32_32x32x16_bf16 v[16:31], v[72:75], v[68:71], v[16:31]
	v_mfma_f32_32x32x16_bf16 v[0:15], v[76:79], v[68:71], v[0:15]
	v_xor_b32_e32 v225, s5, v224
	ds_read_b128 v[244:247], v225
	ds_read_b128 v[248:251], v225 offset:4096
	ds_read_b128 v[72:75], v225 offset:8192
	ds_read_b128 v[76:79], v225 offset:12288
	s_waitcnt lgkmcnt(4)
	v_mfma_f32_32x32x16_bf16 v[48:63], v[228:231], v[176:179], v[48:63]
	v_mfma_f32_32x32x16_bf16 v[32:47], v[232:235], v[176:179], v[32:47]
	v_mfma_f32_32x32x16_bf16 v[16:31], v[236:239], v[176:179], v[16:31]
	v_mfma_f32_32x32x16_bf16 v[0:15], v[240:243], v[176:179], v[0:15]
	s_waitcnt vmcnt(0) lgkmcnt(0)
	s_barrier
	v_mfma_f32_32x32x16_bf16 v[48:63], v[244:247], v[180:183], v[48:63]
	v_mfma_f32_32x32x16_bf16 v[32:47], v[248:251], v[180:183], v[32:47]
	v_mfma_f32_32x32x16_bf16 v[16:31], v[72:75], v[180:183], v[16:31]
	v_mfma_f32_32x32x16_bf16 v[0:15], v[76:79], v[180:183], v[0:15]
	s_cbranch_scc1 .LBB0_817

.LBB0_817:
	s_setprio 0
	s_add_i32 s0, s29, 0x10000
	v_add3_u32 v113, s0, v215, v216
	v_xor_b32_e32 v68, 32, v113
	ds_read_b128 v[146:149], v68
	v_xor_b32_e32 v68, 64, v113
	ds_read_b128 v[64:67], v113
	ds_read_b128 v[150:153], v68
	v_xor_b32_e32 v68, 0x60, v113
	ds_read_b128 v[154:157], v68
	s_waitcnt lgkmcnt(2)
	v_mfma_f32_32x32x16_bf16 v[64:79], v[64:67], v[142:145], 0
	v_mfma_f32_32x32x16_bf16 v[64:79], v[146:149], v[138:141], v[64:79]
	v_xor_b32_e32 v138, 0x80, v113
	v_xor_b32_e32 v142, 0xa0, v113
	ds_read_b128 v[138:141], v138
	ds_read_b128 v[142:145], v142
	s_waitcnt lgkmcnt(3)
	v_mfma_f32_32x32x16_bf16 v[64:79], v[150:153], v[134:137], v[64:79]
	s_waitcnt lgkmcnt(2)
	v_mfma_f32_32x32x16_bf16 v[64:79], v[154:157], v[130:133], v[64:79]
	v_xor_b32_e32 v130, 0xc0, v113
	v_xor_b32_e32 v134, 0xe0, v113
	ds_read_b128 v[130:133], v130
	ds_read_b128 v[134:137], v134
	s_waitcnt lgkmcnt(3)
	v_mfma_f32_32x32x16_bf16 v[64:79], v[138:141], v[126:129], v[64:79]
	s_waitcnt lgkmcnt(2)
	v_mfma_f32_32x32x16_bf16 v[64:79], v[142:145], v[122:125], v[64:79]
	v_xor_b32_e32 v122, 0x100, v113
	v_xor_b32_e32 v126, 0x120, v113
	ds_read_b128 v[122:125], v122
	ds_read_b128 v[126:129], v126
	s_waitcnt lgkmcnt(3)
	v_mfma_f32_32x32x16_bf16 v[64:79], v[130:133], v[118:121], v[64:79]
	s_waitcnt lgkmcnt(2)
	v_mfma_f32_32x32x16_bf16 v[64:79], v[134:137], v[114:117], v[64:79]
	v_xor_b32_e32 v114, 0x140, v113
	v_xor_b32_e32 v118, 0x160, v113
	ds_read_b128 v[114:117], v114
	ds_read_b128 v[118:121], v118
	s_waitcnt lgkmcnt(3)
	v_mfma_f32_32x32x16_bf16 v[64:79], v[122:125], v[108:111], v[64:79]
	s_waitcnt lgkmcnt(2)
	v_mfma_f32_32x32x16_bf16 v[64:79], v[126:129], v[104:107], v[64:79]
	v_xor_b32_e32 v104, 0x180, v113
	v_xor_b32_e32 v108, 0x1a0, v113
	ds_read_b128 v[104:107], v104
	ds_read_b128 v[108:111], v108
	s_waitcnt lgkmcnt(3)
	v_mfma_f32_32x32x16_bf16 v[64:79], v[114:117], v[100:103], v[64:79]
	s_waitcnt lgkmcnt(2)
	v_mfma_f32_32x32x16_bf16 v[64:79], v[118:121], v[96:99], v[64:79]
	v_xor_b32_e32 v96, 0x1c0, v113
	v_xor_b32_e32 v100, 0x1e0, v113
	ds_read_b128 v[96:99], v96
	ds_read_b128 v[100:103], v100
	s_waitcnt lgkmcnt(3)
	v_mfma_f32_32x32x16_bf16 v[64:79], v[104:107], v[92:95], v[64:79]
	s_waitcnt lgkmcnt(2)
	v_mfma_f32_32x32x16_bf16 v[64:79], v[108:111], v[88:91], v[64:79]
	s_waitcnt lgkmcnt(1)
	v_mfma_f32_32x32x16_bf16 v[64:79], v[96:99], v[84:87], v[64:79]
	s_waitcnt lgkmcnt(0)
	v_mfma_f32_32x32x16_bf16 v[64:79], v[100:103], v[80:83], v[64:79]
	v_exp_f32_e32 v80, v214
	s_add_i32 s29, s29, 0x18000
	v_add3_u32 v88, s29, v202, v213
	v_xor_b32_e32 v84, s28, v88
	s_nop 7
	v_pk_mul_f32 v[64:65], v[80:81], v[64:65] op_sel_hi:[0,1]
	v_pk_mul_f32 v[66:67], v[80:81], v[66:67] op_sel_hi:[0,1]
	v_pk_mul_f32 v[68:69], v[80:81], v[68:69] op_sel_hi:[0,1]
	v_pk_mul_f32 v[70:71], v[80:81], v[70:71] op_sel_hi:[0,1]
	v_pk_mul_f32 v[72:73], v[80:81], v[72:73] op_sel_hi:[0,1]
	v_pk_mul_f32 v[74:75], v[80:81], v[74:75] op_sel_hi:[0,1]
	v_pk_mul_f32 v[76:77], v[80:81], v[76:77] op_sel_hi:[0,1]
	v_pk_mul_f32 v[78:79], v[80:81], v[78:79] op_sel_hi:[0,1]
	v_cvt_pk_bf16_f32 v64, v64, v65
	v_cvt_pk_bf16_f32 v65, v66, v67
	v_cvt_pk_bf16_f32 v66, v68, v69
	v_cvt_pk_bf16_f32 v67, v70, v71
	v_cvt_pk_bf16_f32 v68, v72, v73
	v_cvt_pk_bf16_f32 v69, v74, v75
	v_cvt_pk_bf16_f32 v70, v76, v77
	v_cvt_pk_bf16_f32 v71, v78, v79
	ds_write_b128 v175, v[64:67]
	ds_write_b128 v175, v[68:71] offset:1024
	ds_read_b128 v[72:75], v84
	ds_read_b128 v[76:79], v84 offset:4096
	ds_read_b128 v[80:83], v84 offset:8192
	ds_read_b128 v[84:87], v84 offset:12288
	s_waitcnt lgkmcnt(3)
	v_mfma_f32_32x32x16_bf16 v[48:63], v[72:75], v[64:67], v[48:63]
	v_readfirstlane_b32 s4, v193
	s_lshl_b32 s55, s4, 5
	s_add_i32 s0, s55, 0
	s_add_i32 s0, s0, 0x25000
	v_cmp_gt_u32_e32 vcc, 32, v191
	s_waitcnt lgkmcnt(2)
	v_mfma_f32_32x32x16_bf16 v[32:47], v[76:79], v[64:67], v[32:47]
	s_waitcnt lgkmcnt(1)
	v_mfma_f32_32x32x16_bf16 v[16:31], v[80:83], v[64:67], v[16:31]
	v_xor_b32_e32 v80, s27, v88
	s_waitcnt lgkmcnt(0)
	v_mfma_f32_32x32x16_bf16 v[0:15], v[84:87], v[64:67], v[0:15]
	ds_read_b128 v[64:67], v80
	ds_read_b128 v[72:75], v80 offset:4096
	ds_read_b128 v[76:79], v80 offset:8192
	ds_read_b128 v[80:83], v80 offset:12288
	s_waitcnt lgkmcnt(0)
	s_barrier
	s_waitcnt lgkmcnt(3)
	v_mfma_f32_32x32x16_bf16 v[48:63], v[64:67], v[68:71], v[48:63]
	ds_read_b128 v[64:67], v174
	s_waitcnt lgkmcnt(3)
	v_mfma_f32_32x32x16_bf16 v[32:47], v[72:75], v[68:71], v[32:47]
	s_waitcnt lgkmcnt(2)
	v_mfma_f32_32x32x16_bf16 v[16:31], v[76:79], v[68:71], v[16:31]
	s_waitcnt lgkmcnt(1)
	v_mfma_f32_32x32x16_bf16 v[0:15], v[80:83], v[68:71], v[0:15]
	v_xor_b32_e32 v80, s26, v88
	ds_read_b128 v[68:71], v80
	ds_read_b128 v[72:75], v80 offset:4096
	ds_read_b128 v[76:79], v80 offset:8192
	ds_read_b128 v[80:83], v80 offset:12288
	s_waitcnt lgkmcnt(3)
	v_mfma_f32_32x32x16_bf16 v[48:63], v[68:71], v[64:67], v[48:63]
	s_waitcnt lgkmcnt(2)
	v_mfma_f32_32x32x16_bf16 v[32:47], v[72:75], v[64:67], v[32:47]
	s_waitcnt lgkmcnt(1)
	v_mfma_f32_32x32x16_bf16 v[16:31], v[76:79], v[64:67], v[16:31]
	s_waitcnt lgkmcnt(0)
	v_mfma_f32_32x32x16_bf16 v[0:15], v[80:83], v[64:67], v[0:15]
	ds_read_b128 v[64:67], v174 offset:1024
	v_xor_b32_e32 v80, s5, v88
	ds_read_b128 v[68:71], v80
	ds_read_b128 v[72:75], v80 offset:4096
	ds_read_b128 v[76:79], v80 offset:8192
	ds_read_b128 v[80:83], v80 offset:12288
	s_waitcnt vmcnt(0)
	s_waitcnt lgkmcnt(0)
	s_barrier
	v_mfma_f32_32x32x16_bf16 v[48:63], v[68:71], v[64:67], v[48:63]
	s_load_dwordx2 s[20:21], s[66:67], 0x150
	v_mfma_f32_32x32x16_bf16 v[32:47], v[72:75], v[64:67], v[32:47]
	v_mfma_f32_32x32x16_bf16 v[16:31], v[76:79], v[64:67], v[16:31]
	v_mfma_f32_32x32x16_bf16 v[0:15], v[80:83], v[64:67], v[0:15]
	v_mov_b32_e32 v64, s0
	ds_read_b128 v[64:67], v64
	s_waitcnt lgkmcnt(0)
	v_readfirstlane_b32 s7, v64
	s_nop 3
	v_mul_f32_e32 v64, v49, v49
	v_fmac_f32_e32 v64, v48, v48
	v_fmac_f32_e32 v64, v50, v50
	v_fmac_f32_e32 v64, v51, v51
	v_fmac_f32_e32 v64, v52, v52
	v_fmac_f32_e32 v64, v53, v53
	v_fmac_f32_e32 v64, v54, v54
	v_fmac_f32_e32 v64, v55, v55
	v_fmac_f32_e32 v64, v56, v56
	v_fmac_f32_e32 v64, v57, v57
	v_fmac_f32_e32 v64, v58, v58
	v_fmac_f32_e32 v64, v59, v59
	v_fmac_f32_e32 v64, v60, v60
	v_fmac_f32_e32 v64, v61, v61
	v_fmac_f32_e32 v64, v62, v62
	v_fmac_f32_e32 v64, v63, v63
	v_fmac_f32_e32 v64, v32, v32
	v_fmac_f32_e32 v64, v33, v33
	v_fmac_f32_e32 v64, v34, v34
	v_fmac_f32_e32 v64, v35, v35
	v_fmac_f32_e32 v64, v36, v36
	v_fmac_f32_e32 v64, v37, v37
	v_fmac_f32_e32 v64, v38, v38
	v_fmac_f32_e32 v64, v39, v39
	v_fmac_f32_e32 v64, v40, v40
	v_fmac_f32_e32 v64, v41, v41
	v_fmac_f32_e32 v64, v42, v42
	v_fmac_f32_e32 v64, v43, v43
	v_fmac_f32_e32 v64, v44, v44
	v_fmac_f32_e32 v64, v45, v45
	v_fmac_f32_e32 v64, v46, v46
	v_fmac_f32_e32 v64, v47, v47
	v_fmac_f32_e32 v64, v16, v16
	v_fmac_f32_e32 v64, v17, v17
	v_fmac_f32_e32 v64, v18, v18
	v_fmac_f32_e32 v64, v19, v19
	v_fmac_f32_e32 v64, v20, v20
	v_fmac_f32_e32 v64, v21, v21
	v_fmac_f32_e32 v64, v22, v22
	v_fmac_f32_e32 v64, v23, v23
	v_fmac_f32_e32 v64, v24, v24
	v_fmac_f32_e32 v64, v25, v25
	v_fmac_f32_e32 v64, v26, v26
	v_fmac_f32_e32 v64, v27, v27
	v_fmac_f32_e32 v64, v28, v28
	v_fmac_f32_e32 v64, v29, v29
	v_fmac_f32_e32 v64, v30, v30
	v_fmac_f32_e32 v64, v31, v31
	v_fmac_f32_e32 v64, v0, v0
	v_fmac_f32_e32 v64, v1, v1
	v_fmac_f32_e32 v64, v2, v2
	v_fmac_f32_e32 v64, v3, v3
	v_fmac_f32_e32 v64, v4, v4
	v_fmac_f32_e32 v64, v5, v5
	v_fmac_f32_e32 v64, v6, v6
	v_fmac_f32_e32 v64, v7, v7
	v_fmac_f32_e32 v64, v8, v8
	v_fmac_f32_e32 v64, v9, v9
	v_fmac_f32_e32 v64, v10, v10
	v_fmac_f32_e32 v64, v11, v11
	v_readfirstlane_b32 s6, v65
	v_fmac_f32_e32 v64, v12, v12
	v_mov_b32_e32 v65, v192
	v_fmac_f32_e32 v64, v13, v13
	v_fmac_f32_e32 v64, v14, v14
	v_lshlrev_b32_e32 v65, 2, v65
	v_fmac_f32_e32 v64, v15, v15
	v_bitop3_b32 v65, v65, s33, v203 bitop3:0x6c
	ds_bpermute_b32 v65, v65, v64
	v_readfirstlane_b32 s24, v66
	v_readfirstlane_b32 s22, v67
	s_and_saveexec_b64 s[0:1], vcc
	s_cbranch_execz .LBB0_819
	s_lshl_b32 s5, s4, 7
	s_add_i32 s5, s5, 0
	s_waitcnt lgkmcnt(0)
	v_add_f32_e32 v64, v64, v65
	v_lshl_add_u32 v65, v189, 2, s5
	ds_write_b32 v65, v64
